# v38 stacked plus GEMM loops with static s_setprio for waves 4-7 instead of per-segment toggles
# speedup vs baseline: 1.0020x; 1.0020x over previous
; #define LAS __attribute__((address_space(3)))
; __device__ __forceinline__ void attn_fast(const Ptrs& P, LAS unsigned char* lds, int G, int bid) {
;     const int tid = threadIdx.x, lane = tid & 63, w = __builtin_amdgcn_readfirstlane(tid >> 6), fr = lane & 15, fq = lane >> 4, qi = fr >> 2, hh = fr & 3;
;     LAS float* IMP = (LAS float*)(lds + 98304) + w * (8 * 132);
;     LAS unsigned* SELM = (LAS unsigned*)(lds + 132096);
;     const h16* U = (const h16*)(P.ws + WS_U); h16* Y = (h16*)(P.ws + WS_YACC);
;     const float SC = 0.08838834764831845f * 1.4426950408889634f;
;     const int NEGBIG = -(1 << 30);
;     unsigned kl[4]; kl[0] = (unsigned)lane; kl[1] = kl[2] = kl[3] = 0u;
;     const int vz = (4 * fq + (fr >> 2)) & 7;
;     const unsigned vl0 = (unsigned)((4 * fq + (fr >> 2)) * 256 + 8 * (fr & 1) + 16 * ((fr >> 1) & 1));
;     const int nunits = (512 + G - 1) / G;
; #pragma unroll 1
;     for (int ui = 0; ui < nunits; ++ui) {
;         int b, qb;
;         if (G == 256) { const int idx = (bid & 1) * 32 + (bid >> 3); b = (bid & 7) >> 1; qb = ui == 0 ? 127 - idx : idx; }
;         else { const int u = ui * G + bid; if (u >= 512) break;
.LBB0_501:
.LBB0_502:
	s_setprio 0
	s_cmp_lt_i32 s26, 6
	s_cselect_b64 s[0:1], -1, 0
	s_cmp_gt_i32 s27, 5
	s_cselect_b64 s[4:5], -1, 0
	s_and_b64 s[0:1], s[0:1], s[4:5]
	s_andn2_b64 vcc, exec, s[0:1]
	s_cbranch_vccnz .LBB0_694
	s_abs_i32 s1, s95
	v_cvt_f32_u32_e32 v2, s1
	s_sub_i32 s5, 0, s1
	s_add_i32 s3, s95, 0x1ff
	s_xor_b32 s4, s3, s95
	v_rcp_iflag_f32_e32 v2, v2
	s_abs_i32 s3, s3
	s_ashr_i32 s4, s4, 31
	v_readfirstlane_b32 s0, v1
	v_mul_f32_e32 v2, 0x4f7ffffe, v2
	v_cvt_u32_f32_e32 v2, v2
	v_writelane_b32 v243, s68, 0
	s_mov_b32 s65, 0
	v_readfirstlane_b32 s6, v2
	s_mul_i32 s5, s5, s6
	s_mul_hi_u32 s5, s6, s5
	s_add_i32 s6, s6, s5
	s_mul_hi_u32 s5, s3, s6
	s_mul_i32 s6, s5, s1
	s_sub_i32 s3, s3, s6
	s_add_i32 s7, s5, 1
	s_sub_i32 s6, s3, s1
	s_cmp_ge_u32 s3, s1
	s_cselect_b32 s5, s7, s5
	s_cselect_b32 s3, s6, s3
	s_add_i32 s6, s5, 1
	s_cmp_ge_u32 s3, s1
	s_cselect_b32 s1, s6, s5
	v_writelane_b32 v243, s69, 1
	s_xor_b32 s1, s1, s4
	v_writelane_b32 v243, s78, 2
	s_sub_i32 s12, s1, s4
	s_cmp_lt_i32 s12, 1
	v_writelane_b32 v243, s79, 3
	v_writelane_b32 v243, s76, 4
	s_cbranch_scc1 .LBB0_630
	s_lshr_b32 s0, s0, 6
	s_cmp_lt_u32 s0, 4
	s_cbranch_scc1 .Lprio_skip
	s_setprio 1
